# dense attention loops keep m+threshold and -m*c in registers (updated only in the rare rescale path): 4 fewer VALU ops per iteration
# speedup vs baseline: 1.0456x; 1.0044x over previous
; template <int DQK, bool BAND, int QT> ...
;     ...
;   const int tid = tid_(), lane = tid & 63, w = tid >> 6, h = lane >> 5, ql = lane & 31;
;   float* bias_l = (float*)(lds + 2 * ST);
;   if (BAND) { if (tid < 129) bias_l[tid] = bias_g[tid]; }
;   bf16x8 qf[QT][NKS];
; #pragma unroll
;   for (int qt = 0; qt < QT; ++qt)
; #pragma unroll
;     for (int ks = 0; ks < NKS; ++ks) qf[qt][ks] = *(const bf16x8*)(Q + (size_t)(w * WQ + qt * 32 + ql) * DQK + ks * 16 + h * 8);
;   f32x16 o[2][QT];
; #pragma unroll
;   for (int a = 0; a < 2; ++a)
; #pragma unroll
;     for (int b = 0; b < QT; ++b)
; #pragma unroll
;       for (int r = 0; r < 16; ++r) o[a][b][r] = 0.f;
;   float m[QT], l[QT];
; #pragma unroll
;   for (int qt = 0; qt < QT; ++qt) { m[qt] = -1e30f; l[qt] = 0.f; }
;   u32x4 rk[NKL], rv[2];
;   const int vrow0 = tid >> 3, vch = tid & 7;
;   unsigned klds[NKL];
; #pragma unroll
;   for (int i = 0; i < NKL; ++i) { const int idx = tid + i * 256, kr = idx / KV4, kc = idx - kr * KV4; klds[i] = kr * KROW + kc * 16; }
;   const unsigned koff0 = (unsigned)tid * 16u;
;   const unsigned voff0 = (unsigned)(vrow0 * ldv + vch * 8) * 2u, vstep = (unsigned)(32 * ldv) * 2u;
;   const unsigned vlds0 = KST + vrow0 * LROW + vch * 16;
;   auto gload = [&](int kt) {
;     const char* kb = (const char*)Kp + (size_t)kt * (DQK * 2);
;     const char* vb = (const char*)Vt + (size_t)kt * 2;
; #pragma unroll
;     for (int i = 0; i < NKL; ++i) rk[i] = *(const u32x4*)(kb + (koff0 + i * 4096u));
; DI void phase_attn(const Ctx& c) {
;     ...
;     } else if (item < n_mla + n_gqa) {
;       const int i2 = item - n_mla;
;       const int hq = i2 & 7, rest = i2 >> 3, seq = rest / nqb, qb = rest - seq * nqb;
;       const size_t hs = (size_t)(seq * 8 + hq) * S, ks = (size_t)(seq * 2 + (hq >> 2)) * S;
;       if (ATT_PIPE) attn_dense<64>(wsb(c, OFF_QC) + (hs + qb * QBLK) * 64, wsb(c, OFF_KC) + ks * 64, wsb(c, OFF_VTC) + (size_t)(seq * 2 + (hq >> 2)) * 64 * (S + 64), S + 64,
;                      S, 0.125f * LOG2E, wsb(c, OFF_OC) + ((size_t)seq * S + qb * QBLK) * LDO + hq * 64, LDO, c.lds);
;       else attn_item<64, false, AQT>(wsb(c, OFF_QC) + (hs + qb * QBLK) * 64, wsb(c, OFF_KC) + ks * 64, wsb(c, OFF_VTC) + (size_t)(seq * 2 + (hq >> 2)) * 64 * (S + 64), S + 64,
;                      0, S, 0, nullptr, 0.125f * LOG2E, wsb(c, OFF_OC) + ((size_t)seq * S + qb * QBLK) * LDO + hq * 64, LDO, nullptr, 0, c.lds);
.LBB0_826:
	s_and_b64 vcc, exec, s[0:1]
	s_cbranch_vccz .LBB0_838
	v_readlane_b32 s0, v249, 58
	s_sub_i32 s0, s26, s0
	s_ashr_i32 s1, s0, 3
	s_ashr_i32 s7, s0, 31
	s_abs_i32 s0, s1
	v_readlane_b32 s2, v248, 3
	s_mul_hi_u32 s2, s0, s2
	v_readlane_b32 s5, v248, 2
	s_mul_i32 s3, s2, s5
	s_sub_i32 s0, s0, s3
	s_add_i32 s3, s2, 1
	s_sub_i32 s4, s0, s5
	s_cmp_ge_u32 s0, s5
	s_cselect_b32 s2, s3, s2
	s_cselect_b32 s0, s4, s0
	s_add_i32 s3, s2, 1
	s_cmp_ge_u32 s0, s5
	s_cselect_b32 s0, s3, s2
	s_xor_b32 s40, s0, s7
	s_sub_i32 s0, s40, s7
	s_lshl_b32 s2, s0, s60
	s_sub_i32 s1, s1, s2
	s_lshl_b32 s2, s0, 3
	v_readlane_b32 s3, v249, 31
	s_or_b32 s2, s2, s3
	s_lshl_b32 s4, s0, 1
	v_readlane_b32 s41, v250, 44
	s_ashr_i32 s3, s2, 31
	s_or_b32 s26, s4, s41
	s_lshl_b32 s4, s1, 8
	s_lshl_b64 s[2:3], s[2:3], s20
	s_ashr_i32 s27, s26, 31
	s_ashr_i32 s5, s4, 31
	s_add_u32 s2, s2, s4
	s_addc_u32 s3, s3, s5
	s_lshl_b64 s[2:3], s[2:3], 7
	v_readlane_b32 s1, v250, 53
	s_add_u32 s34, s1, s2
	v_readlane_b32 s1, v250, 54
	s_addc_u32 s35, s1, s3
	v_readlane_b32 s1, v248, 1
	s_lshl_b64 s[2:3], s[26:27], s1
	v_readlane_b32 s1, v250, 55
	s_add_u32 s38, s1, s2
	v_readlane_b32 s1, v250, 56
	v_mov_b32_e32 v5, v199
	s_addc_u32 s39, s1, s3
	v_readlane_b32 s1, v249, 61
	v_readlane_b32 s6, v249, 63
	v_lshlrev_b32_e32 v2, 4, v5
	v_ashrrev_i32_e32 v18, 3, v5
	s_mul_hi_i32 s27, s26, s1
	s_mul_i32 s26, s26, s1
	v_and_b32_e32 v4, 0x70, v2
	v_mul_lo_u32 v0, v18, s6
	v_bfe_u32 v196, v5, 5, 1
	v_and_b32_e32 v180, 0xffffffdf, v5
	s_lshl_b64 s[26:27], s[26:27], 1
	v_readlane_b32 s42, v250, 28
	v_or_b32_e32 v6, v4, v0
	s_waitcnt vmcnt(16)
	v_or_b32_e32 v178, 32, v5
	v_lshlrev_b32_e32 v0, 4, v196
	v_ashrrev_i32_e32 v181, 31, v180
	v_readlane_b32 s43, v250, 29
	s_add_u32 s26, s42, s26
	v_ashrrev_i32_e32 v179, 31, v178
	v_lshlrev_b64 v[12:13], 7, v[180:181]
	v_lshl_add_u64 v[16:17], s[34:35], 0, v[0:1]
	s_addc_u32 s27, s43, s27
	v_lshlrev_b64 v[14:15], 7, v[178:179]
	v_lshl_add_u64 v[12:13], v[16:17], 0, v[12:13]
	v_add_u32_e32 v8, 0x1000, v2
	global_load_dwordx4 v[130:133], v2, s[38:39]
	global_load_dwordx4 v[134:137], v8, s[38:39]
	v_add_u32_e32 v10, s1, v6
	global_load_dwordx4 v[138:141], v6, s[26:27]
	global_load_dwordx4 v[142:145], v10, s[26:27]
	v_lshl_add_u64 v[14:15], v[16:17], 0, v[14:15]
	global_load_dwordx4 v[146:149], v[12:13], off
	global_load_dwordx4 v[150:153], v[12:13], off offset:32
	global_load_dwordx4 v[154:157], v[12:13], off offset:64
	global_load_dwordx4 v[158:161], v[12:13], off offset:96
	global_load_dwordx4 v[162:165], v[14:15], off
	global_load_dwordx4 v[166:169], v[14:15], off offset:32
	global_load_dwordx4 v[170:173], v[14:15], off offset:64
	global_load_dwordx4 v[174:177], v[14:15], off offset:96
	v_ashrrev_i32_e32 v19, 31, v5
	v_add_u32_e32 v20, 0x100, v5
	v_lshrrev_b32_e32 v13, 29, v19
	v_ashrrev_i32_e32 v14, 31, v20
	v_add_u32_e32 v13, v5, v13
	v_lshrrev_b32_e32 v14, 29, v14
	v_mad_u64_u32 v[182:183], s[26:27], v18, s16, v[4:5]
	v_ashrrev_i32_e32 v13, 3, v13
	v_add_u32_e32 v4, v20, v14
	v_lshlrev_b32_e32 v16, 7, v13
	v_ashrrev_i32_e32 v17, 3, v4
	v_lshlrev_b32_e32 v15, 4, v20
	v_sub_u32_e32 v4, v2, v16
	v_lshlrev_b32_e32 v16, 7, v17
	v_mad_u64_u32 v[184:185], s[26:27], v13, s16, v[4:5]
	v_sub_u32_e32 v4, v15, v16
	v_mad_u64_u32 v[186:187], s[26:27], v17, s16, v[4:5]
	s_lshl_b32 s26, s40, 1
	s_or_b32 s26, s41, s26
	s_lshl_b32 s7, s7, 1
	s_sub_i32 s7, s26, s7
	v_readlane_b32 s26, v248, 4
	v_and_b32_e32 v12, 31, v5
	v_add_u32_e32 v4, 0, v184
	s_mul_hi_i32 s27, s26, s7
	s_mul_i32 s7, s26, s7
	v_add_u32_e32 v14, 0, v182
	v_add_u32_e32 v13, 0, v186
	v_mul_u32_u24_e32 v183, 0x90, v12
	v_lshlrev_b32_e32 v12, 1, v5
	s_add_u32 s26, s7, 0x179d5980
	s_waitcnt vmcnt(11)
	ds_write_b128 v4, v[130:133]
	s_waitcnt vmcnt(10)
	ds_write_b128 v13, v[134:137]
	s_waitcnt vmcnt(9)
	ds_write_b128 v14, v[138:141] offset:9216
	s_waitcnt vmcnt(8)
; template <int DQK, bool BAND, int QT> ...
;     ...
;   float m[QT], l[QT];
; #pragma unroll
;   for (int qt = 0; qt < QT; ++qt) { m[qt] = -1e30f; l[qt] = 0.f; }
;   u32x4 rk[NKL], rv[2];
;   const int vrow0 = tid >> 3, vch = tid & 7;
;   unsigned klds[NKL];
; #pragma unroll
;   for (int i = 0; i < NKL; ++i) { const int idx = tid + i * 256, kr = idx / KV4, kc = idx - kr * KV4; klds[i] = kr * KROW + kc * 16; }
;   const unsigned koff0 = (unsigned)tid * 16u;
;   const unsigned voff0 = (unsigned)(vrow0 * ldv + vch * 8) * 2u, vstep = (unsigned)(32 * ldv) * 2u;
;   const unsigned vlds0 = KST + vrow0 * LROW + vch * 16;
;   auto gload = [&](int kt) {
;     const char* kb = (const char*)Kp + (size_t)kt * (DQK * 2);
;     const char* vb = (const char*)Vt + (size_t)kt * 2;
; #pragma unroll
;     for (int i = 0; i < NKL; ++i) rk[i] = *(const u32x4*)(kb + (koff0 + i * 4096u));
; #pragma unroll
;     for (int i = 0; i < 2; ++i) rv[i] = *(const u32x4*)(vb + (voff0 + i * vstep));
;   };
;   auto lstore = [&](char* st) {
; #pragma unroll
;     for (int i = 0; i < NKL; ++i) *(u32x4*)(st + klds[i]) = rk[i];
; #pragma unroll
;     for (int i = 0; i < 2; ++i) *(u32x4*)(st + vlds0 + i * 32 * LROW) = rv[i];
;   };
;   gload(kbeg);
;   lstore(lds);
;   __syncthreads();
;   const int pr = (ql & ~12) | ((ql & 4) << 1) | ((ql & 8) >> 1);
;   const int k_rd = pr * KROW + h * 16;
;   const int v_rd = KST + ql * LROW + h * 16;
;   const int qw0 = q0 + w * WQ;
	ds_write_b128 v14, v[142:145] offset:13824
	v_and_b32_e32 v4, 19, v5
	v_lshrrev_b32_e32 v5, 1, v5
	v_and_b32_e32 v12, 8, v12
	v_and_b32_e32 v5, 4, v5
	s_addc_u32 s27, s27, 0
	v_or3_b32 v4, v4, v12, v5
	v_cmp_lt_i32_e32 vcc, v221, v220
	s_add_u32 s2, s2, 0x175d7900
	v_mov_b32_e32 v3, v1
	v_mov_b32_e32 v9, v1
	v_mov_b32_e32 v7, v1
	v_mov_b32_e32 v11, v1
	v_mul_u32_u24_e32 v185, 0x90, v4
	v_cndmask_b32_e32 v4, v219, v221, vcc
	s_addc_u32 s3, s3, 0
	v_mov_b32_e32 v50, v1
	v_mov_b32_e32 v51, v1
	v_lshlrev_b32_e32 v179, 2, v4
	v_lshl_add_u64 v[188:189], s[26:27], 0, v[6:7]
	v_lshl_add_u64 v[190:191], s[26:27], 0, v[10:11]
	v_lshl_add_u64 v[192:193], s[2:3], 0, v[2:3]
	v_lshl_add_u64 v[194:195], s[2:3], 0, v[8:9]
	v_mov_b32_e32 v52, v1
	v_mov_b32_e32 v53, v1
	v_mov_b32_e32 v54, v1
	v_mov_b32_e32 v55, v1
	v_mov_b32_e32 v56, v1
	v_mov_b32_e32 v57, v1
	v_mov_b32_e32 v58, v1
	v_mov_b32_e32 v59, v1
	v_mov_b32_e32 v60, v1
	v_mov_b32_e32 v61, v1
	v_mov_b32_e32 v62, v1
	v_mov_b32_e32 v63, v1
	v_mov_b32_e32 v64, v1
	v_mov_b32_e32 v65, v1
	v_mov_b64_e32 v[18:19], v[50:51]
	v_mov_b64_e32 v[34:35], v[50:51]
	v_mov_b64_e32 v[2:3], v[50:51]
	s_mov_b32 s1, 0
	s_mov_b32 s6, 64
	v_mov_b32_e32 v197, 0xf149f2ca
	v_mov_b32_e32 v187, 0
	v_mov_b32_e32 v181, 0
	v_mov_b32_e32 v202, 0xf149f2ca
	v_mov_b64_e32 v[20:21], v[52:53]
	v_mov_b64_e32 v[22:23], v[54:55]
	v_mov_b64_e32 v[24:25], v[56:57]
	v_mov_b64_e32 v[26:27], v[58:59]
	v_mov_b64_e32 v[28:29], v[60:61]
	v_mov_b64_e32 v[30:31], v[62:63]
	v_mov_b64_e32 v[32:33], v[64:65]
	v_mov_b64_e32 v[36:37], v[52:53]
	v_mov_b64_e32 v[38:39], v[54:55]
	v_mov_b64_e32 v[40:41], v[56:57]
	v_mov_b64_e32 v[42:43], v[58:59]
	v_mov_b64_e32 v[44:45], v[60:61]
	v_mov_b64_e32 v[46:47], v[62:63]
	v_mov_b64_e32 v[48:49], v[64:65]
	v_mov_b64_e32 v[4:5], v[52:53]
	v_mov_b64_e32 v[6:7], v[54:55]
	v_mov_b64_e32 v[8:9], v[56:57]
	v_mov_b64_e32 v[10:11], v[58:59]
	v_mov_b64_e32 v[12:13], v[60:61]
	v_mov_b64_e32 v[14:15], v[62:63]
	v_mov_b64_e32 v[16:17], v[64:65]
	v_add_u32_e32 v185, v185, v0
	v_add_u32_e32 v183, v183, v0
	v_mbcnt_lo_u32_b32 v254, -1, 0
	v_mbcnt_hi_u32_b32 v254, -1, v254
	v_and_b32_e32 v255, 15, v254
	v_lshrrev_b32_e32 v253, 4, v254
	v_and_b32_e32 v253, 1, v253
	v_cmp_eq_u32_e32 vcc, v255, v253
	v_mov_b32_e32 v253, 0x3f803f80
	s_nop 1
	v_cndmask_b32_e32 v244, 0, v253, vcc
	v_mov_b32_e32 v245, v244
	v_mov_b32_e32 v246, v244
	v_mov_b32_e32 v247, v244
	v_mov_b32_e32 v236, 0
	v_mov_b32_e32 v237, 0
	v_mov_b32_e32 v238, 0
	v_mov_b32_e32 v239, 0
	v_mov_b32_e32 v240, 0
	v_mov_b32_e32 v241, 0
	v_mov_b32_e32 v242, 0
	v_mov_b32_e32 v243, 0
	v_readfirstlane_b32 s38, v199
	s_lshr_b32 s38, s38, 6
	s_lshl_b32 s39, s38, 10
	v_readlane_b32 s25, v249, 63
	v_mov_b32_e32 v253, v199
	v_mul_u32_u24_e32 v254, 0x1c72, v253
	v_lshrrev_b32_e32 v254, 16, v254
	v_mul_u32_u24_e32 v255, 9, v254
	v_sub_u32_e32 v255, v253, v255
	v_min_u32_e32 v255, 7, v255
	v_mul_u32_u24_e32 v254, 0x80, v254
	v_lshl_add_u32 v130, v255, 4, v254
	v_add_u32_e32 v253, 0x100, v199
	v_mul_u32_u24_e32 v254, 0x1c72, v253
	v_lshrrev_b32_e32 v254, 16, v254
	v_mul_u32_u24_e32 v255, 9, v254
	v_sub_u32_e32 v255, v253, v255
	v_min_u32_e32 v255, 7, v255
	v_mul_u32_u24_e32 v254, 0x80, v254
	v_lshl_add_u32 v131, v255, 4, v254
	v_mov_b32_e32 v253, v199
	v_mul_u32_u24_e32 v254, 0x1c72, v253
	v_lshrrev_b32_e32 v254, 16, v254
	v_mul_u32_u24_e32 v255, 9, v254
	v_sub_u32_e32 v255, v253, v255
	v_min_u32_e32 v255, 7, v255
	v_mul_lo_u32 v254, v254, s25
	v_lshl_add_u32 v132, v255, 4, v254
	v_add_u32_e32 v253, 0x100, v199
	v_mul_u32_u24_e32 v254, 0x1c72, v253
	v_lshrrev_b32_e32 v254, 16, v254
	v_mul_u32_u24_e32 v255, 9, v254
	v_sub_u32_e32 v255, v253, v255
	v_min_u32_e32 v255, 7, v255
	v_mul_lo_u32 v254, v254, s25
	v_lshl_add_u32 v133, v255, 4, v254
	v_add_u32_e32 v253, 0x200, v199
	v_mul_u32_u24_e32 v254, 0x1c72, v253
	v_lshrrev_b32_e32 v254, 16, v254
	v_mul_u32_u24_e32 v255, 9, v254
	v_sub_u32_e32 v255, v253, v255
	v_min_u32_e32 v255, 7, v255
	v_mul_u32_u24_e32 v254, 0x80, v254
	v_lshl_add_u32 v134, v255, 4, v254
	v_add_u32_e32 v253, 0x1c0, v199
	v_mul_u32_u24_e32 v254, 0x1c72, v253
	v_lshrrev_b32_e32 v254, 16, v254
	v_mul_u32_u24_e32 v255, 9, v254
	v_sub_u32_e32 v255, v253, v255
	v_min_u32_e32 v255, 7, v255
	v_mul_lo_u32 v254, v254, s25
	v_lshl_add_u32 v135, v255, 4, v254
	v_cmp_gt_u32_e32 vcc, 64, v199
	s_nop 1
	v_cndmask_b32_e32 v134, v135, v134, vcc
	v_readfirstlane_b32 s34, v192
	v_readfirstlane_b32 s35, v193
	s_add_u32 s34, s34, s94
	s_addc_u32 s35, s35, s95
	s_sub_u32 s34, s34, s39
	s_subb_u32 s35, s35, 0
	v_readfirstlane_b32 s26, v188
	v_readfirstlane_b32 s27, v189
	s_add_u32 s26, s26, s94
	s_addc_u32 s27, s27, s95
	s_mul_i32 s42, s38, s25
	s_lshl_b32 s42, s42, 3
	s_sub_u32 s26, s26, s42
	s_subb_u32 s27, s27, 0
	v_mov_b32_e32 v136, 0xf149f2ca
	v_mov_b32_e32 v137, 0xf149f2ca
	v_mov_b32_e32 v138, 0
	v_mov_b32_e32 v139, 0
	s_waitcnt vmcnt(0) lgkmcnt(0)
	s_barrier

; template <int DQK, bool BAND, int QT> ...
;     ...
;         float mx = s[0][qt][0];
; #pragma unroll
;         for (int r = 1; r < 16; ++r) mx = fmaxf(mx, s[0][qt][r]);
; #pragma unroll
;         for (int r = 0; r < 16; ++r) mx = fmaxf(mx, s[1][qt][r]);
;         mx = fmaxf(mx, __shfl_xor(mx, 32));
;         if (__builtin_amdgcn_ballot_w64(mx > m[qt] + th) != 0) {
;           const float mn = fmaxf(m[qt], mx);
;           const float alpha = __builtin_amdgcn_exp2f((m[qt] - mn) * cc);
;           m[qt] = mn;
;           l[qt] *= alpha;
; #pragma unroll
;           for (int r = 0; r < 16; ++r) { o[0][qt][r] *= alpha; o[1][qt][r] *= alpha; }
;         }
.Lgqa_dma_noload:
	s_nop 7
	s_setprio 0
	v_max_f32_e32 v203, v82, v83
	v_max_f32_e32 v253, v114, v115
	v_max3_f32 v203, v203, v84, v85
	v_max3_f32 v253, v253, v116, v117
	v_max3_f32 v203, v203, v86, v87
	v_max3_f32 v253, v253, v118, v119
	v_max3_f32 v203, v203, v88, v89
	v_max3_f32 v253, v253, v120, v121
	v_max3_f32 v203, v203, v90, v91
	v_max3_f32 v253, v253, v122, v123
	v_max3_f32 v203, v203, v92, v93
	v_max3_f32 v253, v253, v124, v125
	v_max3_f32 v203, v203, v94, v95
	v_max3_f32 v253, v253, v126, v127
	v_max3_f32 v203, v203, v96, v97
	v_max3_f32 v253, v253, v128, v129
	v_max3_f32 v203, v203, v66, v67
	v_max3_f32 v253, v253, v98, v99
	v_max3_f32 v203, v203, v68, v69
	v_max3_f32 v253, v253, v100, v101
	v_max3_f32 v203, v203, v70, v71
	v_max3_f32 v253, v253, v102, v103
	v_max3_f32 v203, v203, v72, v73
	v_max3_f32 v253, v253, v104, v105
	v_max3_f32 v203, v203, v74, v75
	v_max3_f32 v253, v253, v106, v107
	v_max3_f32 v203, v203, v76, v77
	v_max3_f32 v253, v253, v108, v109
	v_max3_f32 v203, v203, v78, v79
	v_max3_f32 v253, v253, v110, v111
	v_max3_f32 v203, v203, v80, v81
	v_max3_f32 v253, v253, v112, v113
	v_cmp_gt_f32_e32 vcc, v203, v136
	s_cbranch_vccz .Lgqa_nr0
	ds_bpermute_b32 v254, v179, v203
	s_waitcnt lgkmcnt(0)
	v_max_f32_e32 v254, v254, v254
	v_max_f32_e32 v203, v203, v254
	v_max_f32_e32 v254, v197, v197
	v_max_f32_e32 v203, v254, v203
	v_sub_f32_e32 v197, v197, v203
	v_mul_f32_e32 v197, 0x3e38aa3b, v197
	v_exp_f32_e32 v254, v197
	v_mov_b32_e32 v197, v203
	v_add_f32_e32 v136, 0x42317218, v203
	v_mul_f32_e32 v138, 0xbe38aa3b, v203
	v_pk_mul_f32 v[64:65], v[64:65], v[254:255] op_sel_hi:[1,0]
	v_pk_mul_f32 v[62:63], v[62:63], v[254:255] op_sel_hi:[1,0]
	v_pk_mul_f32 v[60:61], v[60:61], v[254:255] op_sel_hi:[1,0]
	v_pk_mul_f32 v[58:59], v[58:59], v[254:255] op_sel_hi:[1,0]
	v_pk_mul_f32 v[56:57], v[56:57], v[254:255] op_sel_hi:[1,0]
	v_pk_mul_f32 v[54:55], v[54:55], v[254:255] op_sel_hi:[1,0]
	v_pk_mul_f32 v[52:53], v[52:53], v[254:255] op_sel_hi:[1,0]
	v_pk_mul_f32 v[50:51], v[50:51], v[254:255] op_sel_hi:[1,0]
	v_pk_mul_f32 v[48:49], v[48:49], v[254:255] op_sel_hi:[1,0]
	v_pk_mul_f32 v[46:47], v[46:47], v[254:255] op_sel_hi:[1,0]
	v_pk_mul_f32 v[44:45], v[44:45], v[254:255] op_sel_hi:[1,0]
	v_pk_mul_f32 v[42:43], v[42:43], v[254:255] op_sel_hi:[1,0]
	v_pk_mul_f32 v[40:41], v[40:41], v[254:255] op_sel_hi:[1,0]
	v_pk_mul_f32 v[38:39], v[38:39], v[254:255] op_sel_hi:[1,0]
	v_pk_mul_f32 v[36:37], v[36:37], v[254:255] op_sel_hi:[1,0]
	v_pk_mul_f32 v[34:35], v[34:35], v[254:255] op_sel_hi:[1,0]
	v_mbcnt_lo_u32_b32 v255, -1, 0
	v_mbcnt_hi_u32_b32 v255, -1, v255
	v_add_u32_e32 v255, 16, v255
	v_lshlrev_b32_e32 v255, 2, v255
	ds_bpermute_b32 v255, v255, v254
	s_waitcnt lgkmcnt(0)
	v_mul_f32_e32 v240, v240, v254
	v_mul_f32_e32 v241, v241, v255
.Lgqa_nr0:
	v_cmp_gt_f32_e32 vcc, v253, v137
	s_cbranch_vccz .Lgqa_nr1
	ds_bpermute_b32 v254, v179, v253
	s_waitcnt lgkmcnt(0)
	v_max_f32_e32 v254, v254, v254
	v_max_f32_e32 v253, v253, v254
	v_max_f32_e32 v254, v202, v202
	v_max_f32_e32 v253, v254, v253
	v_sub_f32_e32 v202, v202, v253
	v_mul_f32_e32 v202, 0x3e38aa3b, v202
	v_exp_f32_e32 v254, v202
	v_mov_b32_e32 v202, v253
	v_add_f32_e32 v137, 0x42317218, v253
	v_mul_f32_e32 v139, 0xbe38aa3b, v253
	v_pk_mul_f32 v[32:33], v[32:33], v[254:255] op_sel_hi:[1,0]
	v_pk_mul_f32 v[30:31], v[30:31], v[254:255] op_sel_hi:[1,0]
	v_pk_mul_f32 v[28:29], v[28:29], v[254:255] op_sel_hi:[1,0]
	v_pk_mul_f32 v[26:27], v[26:27], v[254:255] op_sel_hi:[1,0]
	v_pk_mul_f32 v[24:25], v[24:25], v[254:255] op_sel_hi:[1,0]
	v_pk_mul_f32 v[22:23], v[22:23], v[254:255] op_sel_hi:[1,0]
	v_pk_mul_f32 v[20:21], v[20:21], v[254:255] op_sel_hi:[1,0]
	v_pk_mul_f32 v[18:19], v[18:19], v[254:255] op_sel_hi:[1,0]
	v_pk_mul_f32 v[16:17], v[16:17], v[254:255] op_sel_hi:[1,0]
	v_pk_mul_f32 v[14:15], v[14:15], v[254:255] op_sel_hi:[1,0]
	v_pk_mul_f32 v[12:13], v[12:13], v[254:255] op_sel_hi:[1,0]
	v_pk_mul_f32 v[10:11], v[10:11], v[254:255] op_sel_hi:[1,0]
	v_pk_mul_f32 v[8:9], v[8:9], v[254:255] op_sel_hi:[1,0]
	v_pk_mul_f32 v[6:7], v[6:7], v[254:255] op_sel_hi:[1,0]
	v_pk_mul_f32 v[4:5], v[4:5], v[254:255] op_sel_hi:[1,0]
	v_pk_mul_f32 v[2:3], v[2:3], v[254:255] op_sel_hi:[1,0]
	v_mbcnt_lo_u32_b32 v255, -1, 0
	v_mbcnt_hi_u32_b32 v255, -1, v255
	v_add_u32_e32 v255, 16, v255
	v_lshlrev_b32_e32 v255, 2, v255
	ds_bpermute_b32 v255, v255, v254
	s_waitcnt lgkmcnt(0)
	v_mul_f32_e32 v236, v236, v254
	v_mul_f32_e32 v237, v237, v255
; DI unsigned pk2(float a, float b) { f32x2 v = {a, b}; bf16x2_t r = __builtin_convertvector(v, bf16x2_t); return __builtin_bit_cast(unsigned, r); }
; template <int DQK, bool BAND, int QT> ...
;     ...
;         const float mc = -m[qt] * cc;
;         float ls = 0.f;
; #pragma unroll
;         for (int a = 0; a < 2; ++a) {
; #pragma unroll
;           for (int r = 0; r < 16; ++r) { const float pv = __builtin_amdgcn_exp2f(fmaf(s[a][qt][r], cc, mc)); s[a][qt][r] = pv; ls += pv; }
; #pragma unroll
;           for (int s2 = 0; s2 < 2; ++s2) {
;             u32x4 pk;
;             pk.x = pk2(s[a][qt][8 * s2 + 0], s[a][qt][8 * s2 + 1]);
;             pk.y = pk2(s[a][qt][8 * s2 + 2], s[a][qt][8 * s2 + 3]);
;             pk.z = pk2(s[a][qt][8 * s2 + 4], s[a][qt][8 * s2 + 5]);
;             pk.w = pk2(s[a][qt][8 * s2 + 6], s[a][qt][8 * s2 + 7]);
;             pf[qt][a * 2 + s2] = __builtin_bit_cast(bf16x8, pk);
;           }
;         }
.Lgqa_nr1:
	v_fmamk_f32 v82, v82, 0x3e38aa3b, v138
	v_fmamk_f32 v114, v114, 0x3e38aa3b, v139
	v_fmamk_f32 v83, v83, 0x3e38aa3b, v138
	v_fmamk_f32 v115, v115, 0x3e38aa3b, v139
	v_fmamk_f32 v84, v84, 0x3e38aa3b, v138
	v_fmamk_f32 v116, v116, 0x3e38aa3b, v139
	v_fmamk_f32 v85, v85, 0x3e38aa3b, v138
	v_fmamk_f32 v117, v117, 0x3e38aa3b, v139
	v_fmamk_f32 v86, v86, 0x3e38aa3b, v138
	v_fmamk_f32 v118, v118, 0x3e38aa3b, v139
	v_fmamk_f32 v87, v87, 0x3e38aa3b, v138
	v_fmamk_f32 v119, v119, 0x3e38aa3b, v139
	v_fmamk_f32 v88, v88, 0x3e38aa3b, v138
	v_fmamk_f32 v120, v120, 0x3e38aa3b, v139
	v_fmamk_f32 v89, v89, 0x3e38aa3b, v138
	v_fmamk_f32 v121, v121, 0x3e38aa3b, v139
	v_exp_f32_e32 v82, v82
	v_exp_f32_e32 v114, v114
	v_exp_f32_e32 v83, v83
	v_exp_f32_e32 v115, v115
	v_exp_f32_e32 v84, v84
	v_exp_f32_e32 v116, v116
	v_exp_f32_e32 v85, v85
	v_exp_f32_e32 v117, v117
	v_exp_f32_e32 v86, v86
	v_exp_f32_e32 v118, v118
	v_exp_f32_e32 v87, v87
	v_exp_f32_e32 v119, v119
	v_exp_f32_e32 v88, v88
	v_exp_f32_e32 v120, v120
	v_exp_f32_e32 v89, v89
	v_exp_f32_e32 v121, v121
	v_fmamk_f32 v90, v90, 0x3e38aa3b, v138
	v_fmamk_f32 v122, v122, 0x3e38aa3b, v139
	v_fmamk_f32 v91, v91, 0x3e38aa3b, v138
	v_fmamk_f32 v123, v123, 0x3e38aa3b, v139
	v_fmamk_f32 v92, v92, 0x3e38aa3b, v138
	v_fmamk_f32 v124, v124, 0x3e38aa3b, v139
	v_fmamk_f32 v93, v93, 0x3e38aa3b, v138
	v_fmamk_f32 v125, v125, 0x3e38aa3b, v139
	v_fmamk_f32 v94, v94, 0x3e38aa3b, v138
	v_fmamk_f32 v126, v126, 0x3e38aa3b, v139
	v_fmamk_f32 v95, v95, 0x3e38aa3b, v138
	v_fmamk_f32 v127, v127, 0x3e38aa3b, v139
	v_fmamk_f32 v96, v96, 0x3e38aa3b, v138
	v_fmamk_f32 v128, v128, 0x3e38aa3b, v139
	v_fmamk_f32 v97, v97, 0x3e38aa3b, v138
	v_fmamk_f32 v129, v129, 0x3e38aa3b, v139
	v_exp_f32_e32 v90, v90
	v_exp_f32_e32 v122, v122
	v_exp_f32_e32 v91, v91
	v_exp_f32_e32 v123, v123
	v_exp_f32_e32 v92, v92
	v_exp_f32_e32 v124, v124
	v_exp_f32_e32 v93, v93
	v_exp_f32_e32 v125, v125
	v_exp_f32_e32 v94, v94
	v_exp_f32_e32 v126, v126
	v_exp_f32_e32 v95, v95
	v_exp_f32_e32 v127, v127
	v_exp_f32_e32 v96, v96
	v_exp_f32_e32 v128, v128
	v_exp_f32_e32 v97, v97
	v_exp_f32_e32 v129, v129
	v_cvt_pk_bf16_f32 v82, v82, v83
	v_cvt_pk_bf16_f32 v114, v114, v115
	v_cvt_pk_bf16_f32 v83, v84, v85
	v_cvt_pk_bf16_f32 v115, v116, v117
	v_cvt_pk_bf16_f32 v84, v86, v87
	v_cvt_pk_bf16_f32 v116, v118, v119
	v_cvt_pk_bf16_f32 v85, v88, v89
	v_cvt_pk_bf16_f32 v117, v120, v121
	v_fmamk_f32 v66, v66, 0x3e38aa3b, v138
	v_fmamk_f32 v98, v98, 0x3e38aa3b, v139
	v_fmamk_f32 v67, v67, 0x3e38aa3b, v138
	v_fmamk_f32 v99, v99, 0x3e38aa3b, v139
	v_fmamk_f32 v68, v68, 0x3e38aa3b, v138
	v_fmamk_f32 v100, v100, 0x3e38aa3b, v139
	v_fmamk_f32 v69, v69, 0x3e38aa3b, v138
	v_fmamk_f32 v101, v101, 0x3e38aa3b, v139
	v_fmamk_f32 v70, v70, 0x3e38aa3b, v138
	v_fmamk_f32 v102, v102, 0x3e38aa3b, v139
	v_fmamk_f32 v71, v71, 0x3e38aa3b, v138
	v_fmamk_f32 v103, v103, 0x3e38aa3b, v139
	v_fmamk_f32 v72, v72, 0x3e38aa3b, v138
	v_fmamk_f32 v104, v104, 0x3e38aa3b, v139
	v_fmamk_f32 v73, v73, 0x3e38aa3b, v138
	v_fmamk_f32 v105, v105, 0x3e38aa3b, v139
	v_exp_f32_e32 v66, v66
	v_exp_f32_e32 v98, v98
	v_exp_f32_e32 v67, v67
	v_exp_f32_e32 v99, v99
	v_exp_f32_e32 v68, v68
	v_exp_f32_e32 v100, v100
	v_exp_f32_e32 v69, v69
	v_exp_f32_e32 v101, v101
	v_exp_f32_e32 v70, v70
	v_exp_f32_e32 v102, v102
	v_exp_f32_e32 v71, v71
	v_exp_f32_e32 v103, v103
	v_exp_f32_e32 v72, v72
	v_exp_f32_e32 v104, v104
	v_exp_f32_e32 v73, v73
	v_exp_f32_e32 v105, v105
	v_cvt_pk_bf16_f32 v90, v90, v91
	v_cvt_pk_bf16_f32 v122, v122, v123
	v_cvt_pk_bf16_f32 v91, v92, v93
	v_cvt_pk_bf16_f32 v123, v124, v125
	v_cvt_pk_bf16_f32 v92, v94, v95
	v_cvt_pk_bf16_f32 v124, v126, v127
	v_cvt_pk_bf16_f32 v93, v96, v97
	v_cvt_pk_bf16_f32 v125, v128, v129
	v_fmamk_f32 v74, v74, 0x3e38aa3b, v138
	v_fmamk_f32 v106, v106, 0x3e38aa3b, v139
	v_fmamk_f32 v75, v75, 0x3e38aa3b, v138
	v_fmamk_f32 v107, v107, 0x3e38aa3b, v139
	v_fmamk_f32 v76, v76, 0x3e38aa3b, v138
	v_fmamk_f32 v108, v108, 0x3e38aa3b, v139
	v_fmamk_f32 v77, v77, 0x3e38aa3b, v138
	v_fmamk_f32 v109, v109, 0x3e38aa3b, v139
	v_fmamk_f32 v78, v78, 0x3e38aa3b, v138
	v_fmamk_f32 v110, v110, 0x3e38aa3b, v139
	v_fmamk_f32 v79, v79, 0x3e38aa3b, v138
	v_fmamk_f32 v111, v111, 0x3e38aa3b, v139
	v_fmamk_f32 v80, v80, 0x3e38aa3b, v138
	v_fmamk_f32 v112, v112, 0x3e38aa3b, v139
	v_fmamk_f32 v81, v81, 0x3e38aa3b, v138
	v_fmamk_f32 v113, v113, 0x3e38aa3b, v139
	v_exp_f32_e32 v74, v74
	v_exp_f32_e32 v106, v106
	v_exp_f32_e32 v75, v75
	v_exp_f32_e32 v107, v107
	v_exp_f32_e32 v76, v76
	v_exp_f32_e32 v108, v108
	v_exp_f32_e32 v77, v77
	v_exp_f32_e32 v109, v109
	v_exp_f32_e32 v78, v78
	v_exp_f32_e32 v110, v110
	v_exp_f32_e32 v79, v79
	v_exp_f32_e32 v111, v111
	v_exp_f32_e32 v80, v80
	v_exp_f32_e32 v112, v112
	v_exp_f32_e32 v81, v81
	v_exp_f32_e32 v113, v113
	v_cvt_pk_bf16_f32 v66, v66, v67
	v_cvt_pk_bf16_f32 v98, v98, v99
	v_cvt_pk_bf16_f32 v67, v68, v69
	v_cvt_pk_bf16_f32 v99, v100, v101
	v_cvt_pk_bf16_f32 v68, v70, v71
	v_cvt_pk_bf16_f32 v100, v102, v103
	v_cvt_pk_bf16_f32 v69, v72, v73
	v_cvt_pk_bf16_f32 v101, v104, v105
	v_cvt_pk_bf16_f32 v74, v74, v75
	v_cvt_pk_bf16_f32 v106, v106, v107
	v_cvt_pk_bf16_f32 v75, v76, v77
	v_cvt_pk_bf16_f32 v107, v108, v109
	v_cvt_pk_bf16_f32 v76, v78, v79
	v_cvt_pk_bf16_f32 v108, v110, v111
	v_cvt_pk_bf16_f32 v77, v80, v81
	v_cvt_pk_bf16_f32 v109, v112, v113
	s_setprio 2
	ds_read_b128 v[86:89], v183 offset:9216
	ds_read_b128 v[94:97], v183 offset:13824
	ds_read_b128 v[70:73], v183 offset:9248
	ds_read_b128 v[78:81], v183 offset:13856
	ds_read_b128 v[118:121], v183 offset:9280
	ds_read_b128 v[126:129], v183 offset:13888
	ds_read_b128 v[102:105], v183 offset:9312
	ds_read_b128 v[110:113], v183 offset:13920
	s_waitcnt lgkmcnt(7)
; #define MFMA(a, b, c) __builtin_amdgcn_mfma_f32_32x32x16_bf16((a), (b), (c), 0, 0, 0)
; template <int DQK, bool BAND, int QT> ...
;     ...
; #pragma unroll
;       for (int ks = 0; ks < 4; ++ks) {
;         const bf16x8 v0 = *(const bf16x8*)(st + v_rd + ks * 32);
;         const bf16x8 v1 = *(const bf16x8*)(st + v_rd + 32 * LROW + ks * 32);
; #pragma unroll
;         for (int qt = 0; qt < QT; ++qt) {
;           o[0][qt] = MFMA(v0, pf[qt][ks], o[0][qt]);
;           o[1][qt] = MFMA(v1, pf[qt][ks], o[1][qt]);
;         }
;       }
;     } else {
;       if (more) lstore(lds + ((it + 1) & 1) * ST);
;     }
;     __syncthreads();
;   }
; #pragma unroll
;   for (int qt = 0; qt < QT; ++qt) {
;     const float lt = l[qt] + __shfl_xor(l[qt], 32);
;     const float inv = __builtin_amdgcn_rcpf(lt);
	v_mfma_f32_32x32x16_bf16 v[50:65], v[86:89], v[82:85], v[50:65]
	v_mfma_f32_32x32x16_bf16 v[18:33], v[86:89], v[114:117], v[18:33]
	s_waitcnt lgkmcnt(6)
	v_mfma_f32_32x32x16_bf16 v[34:49], v[94:97], v[82:85], v[34:49]
	v_mfma_f32_32x32x16_bf16 v[2:17], v[94:97], v[114:117], v[2:17]
	v_mfma_f32_16x16x32_bf16 v[240:243], v[244:247], v[82:85], v[240:243]
	v_mfma_f32_16x16x32_bf16 v[236:239], v[244:247], v[114:117], v[236:239]
	s_waitcnt lgkmcnt(5)
	v_mfma_f32_32x32x16_bf16 v[50:65], v[70:73], v[90:93], v[50:65]
	v_mfma_f32_32x32x16_bf16 v[18:33], v[70:73], v[122:125], v[18:33]
	s_waitcnt lgkmcnt(4)
	v_mfma_f32_32x32x16_bf16 v[34:49], v[78:81], v[90:93], v[34:49]
	v_mfma_f32_32x32x16_bf16 v[2:17], v[78:81], v[122:125], v[2:17]
	v_mfma_f32_16x16x32_bf16 v[240:243], v[244:247], v[90:93], v[240:243]
	v_mfma_f32_16x16x32_bf16 v[236:239], v[244:247], v[122:125], v[236:239]
	s_waitcnt lgkmcnt(3)
	v_mfma_f32_32x32x16_bf16 v[50:65], v[118:121], v[66:69], v[50:65]
	v_mfma_f32_32x32x16_bf16 v[18:33], v[118:121], v[98:101], v[18:33]
	s_waitcnt lgkmcnt(2)
	v_mfma_f32_32x32x16_bf16 v[34:49], v[126:129], v[66:69], v[34:49]
	v_mfma_f32_32x32x16_bf16 v[2:17], v[126:129], v[98:101], v[2:17]
	v_mfma_f32_16x16x32_bf16 v[240:243], v[244:247], v[66:69], v[240:243]
	v_mfma_f32_16x16x32_bf16 v[236:239], v[244:247], v[98:101], v[236:239]
	s_bitcmp1_b32 s1, 0
	s_cselect_b32 s7, -1, 1
	s_mulk_i32 s7, 0x4800
	v_add_u32_e32 v185, s7, v185
	v_add_u32_e32 v183, s7, v183
	s_add_i32 s1, s1, 1
	s_add_i32 s6, s6, 64
	s_waitcnt vmcnt(0) lgkmcnt(0)
	s_barrier
	v_mfma_f32_32x32x16_bf16 v[50:65], v[102:105], v[74:77], v[50:65]
	v_mfma_f32_32x32x16_bf16 v[18:33], v[102:105], v[106:109], v[18:33]
	v_mfma_f32_32x32x16_bf16 v[34:49], v[110:113], v[74:77], v[34:49]
	v_mfma_f32_32x32x16_bf16 v[2:17], v[110:113], v[106:109], v[2:17]
	v_mfma_f32_16x16x32_bf16 v[240:243], v[244:247], v[74:77], v[240:243]
	v_mfma_f32_16x16x32_bf16 v[236:239], v[244:247], v[106:109], v[236:239]
	s_cmp_lg_u32 s21, s1
	s_cbranch_scc1 .Lgqa_top
	s_setprio 0
	s_nop 7
	v_mbcnt_lo_u32_b32 v254, -1, 0
	v_mbcnt_hi_u32_b32 v254, -1, v254
	v_and_b32_e32 v255, 15, v254
	v_lshlrev_b32_e32 v255, 2, v255
	ds_bpermute_b32 v203, v255, v240
	ds_bpermute_b32 v253, v255, v241
	s_waitcnt lgkmcnt(0)
	v_cmp_gt_u32_e32 vcc, 16, v254
	s_nop 1
	v_cndmask_b32_e32 v187, v253, v203, vcc
	v_cmp_gt_u32_e32 vcc, 32, v254
	s_nop 1
	v_cndmask_b32_e32 v187, 0, v187, vcc
	ds_bpermute_b32 v203, v255, v236
	ds_bpermute_b32 v253, v255, v237
	s_waitcnt lgkmcnt(0)
	v_cmp_gt_u32_e32 vcc, 16, v254
	s_nop 1
	v_cndmask_b32_e32 v181, v253, v203, vcc
	v_cmp_gt_u32_e32 vcc, 32, v254
	s_nop 1
	v_cndmask_b32_e32 v181, 0, v181, vcc

; template <int DQK, bool BAND, int QT> ...
;     ...
;   const int tid = tid_(), lane = tid & 63, w = tid >> 6, h = lane >> 5, ql = lane & 31;
;   float* bias_l = (float*)(lds + 2 * ST);
;   if (BAND) { if (tid < 129) bias_l[tid] = bias_g[tid]; }
;   bf16x8 qf[QT][NKS];
; #pragma unroll
;   for (int qt = 0; qt < QT; ++qt)
; #pragma unroll
;     for (int ks = 0; ks < NKS; ++ks) qf[qt][ks] = *(const bf16x8*)(Q + (size_t)(w * WQ + qt * 32 + ql) * DQK + ks * 16 + h * 8);
;   f32x16 o[2][QT];
; #pragma unroll
;   for (int a = 0; a < 2; ++a)
; #pragma unroll
;     for (int b = 0; b < QT; ++b)
; #pragma unroll
;       for (int r = 0; r < 16; ++r) o[a][b][r] = 0.f;
;   float m[QT], l[QT];
; #pragma unroll
;   for (int qt = 0; qt < QT; ++qt) { m[qt] = -1e30f; l[qt] = 0.f; }
;   u32x4 rk[NKL], rv[2];
;   const int vrow0 = tid >> 3, vch = tid & 7;
;   unsigned klds[NKL];
; #pragma unroll
;   for (int i = 0; i < NKL; ++i) { const int idx = tid + i * 256, kr = idx / KV4, kc = idx - kr * KV4; klds[i] = kr * KROW + kc * 16; }
;   const unsigned koff0 = (unsigned)tid * 16u;
;   const unsigned voff0 = (unsigned)(vrow0 * ldv + vch * 8) * 2u, vstep = (unsigned)(32 * ldv) * 2u;
;   const unsigned vlds0 = KST + vrow0 * LROW + vch * 16;
;   auto gload = [&](int kt) {
;     const char* kb = (const char*)Kp + (size_t)kt * (DQK * 2);
;     const char* vb = (const char*)Vt + (size_t)kt * 2;
; #pragma unroll
;     for (int i = 0; i < NKL; ++i) rk[i] = *(const u32x4*)(kb + (koff0 + i * 4096u));
; #pragma unroll
; DI void phase_attn(const Ctx& c) {
;     ...
;     if (item < n_mla) {
;       const int hh = item & 7, rest = item >> 3, seq = rest / nqb, qb = rest - seq * nqb;
;       const size_t hs = (size_t)(seq * 8 + hh) * S;
;       if (ATT_PIPE) attn_dense<96>(wsb(c, OFF_QA) + (hs + qb * QBLK) * 96, wsb(c, OFF_KA) + hs * 96, wsb(c, OFF_VTA) + (size_t)(seq * 8 + hh) * 64 * (S + 64), S + 64,
;                      S, 0.10206207261596577f * LOG2E, wsb(c, OFF_OA) + ((size_t)seq * S + qb * QBLK) * LDO + hh * 64, LDO, c.lds);
;       else attn_item<96, false, AQT>(wsb(c, OFF_QA) + (hs + qb * QBLK) * 96, wsb(c, OFF_KA) + hs * 96, wsb(c, OFF_VTA) + (size_t)(seq * 8 + hh) * 64 * (S + 64), S + 64,
;                      0, S, 0, nullptr, 0.10206207261596577f * LOG2E, wsb(c, OFF_OA) + ((size_t)seq * S + qb * QBLK) * LDO + hh * 64, LDO, nullptr, 0, c.lds);
.LBB0_839:
	s_andn2_b64 vcc, exec, s[0:1]
	s_cbranch_vccnz .LBB0_664
	s_abs_i32 s0, s25
	v_readlane_b32 s1, v248, 3
	s_mul_hi_u32 s1, s0, s1
	v_readlane_b32 s4, v248, 2
	s_mul_i32 s2, s1, s4
	s_sub_i32 s0, s0, s2
	s_ashr_i32 s7, s25, 31
	s_add_i32 s2, s1, 1
	s_sub_i32 s3, s0, s4
	s_cmp_ge_u32 s0, s4
	s_cselect_b32 s1, s2, s1
	s_cselect_b32 s0, s3, s0
	s_add_i32 s2, s1, 1
	s_cmp_ge_u32 s0, s4
	s_cselect_b32 s0, s2, s1
	s_xor_b32 s38, s0, s7
	s_sub_i32 s0, s38, s7
	s_lshl_b32 s1, s0, s60
	s_lshl_b32 s2, s0, 3
	v_readlane_b32 s40, v249, 31
	s_sub_i32 s1, s25, s1
	s_or_b32 s26, s2, s40
	s_ashr_i32 s27, s26, 31
	s_lshl_b32 s4, s1, 8
	s_lshl_b64 s[34:35], s[26:27], s20
	s_ashr_i32 s5, s4, 31
	s_add_u32 s1, s34, s4
	s_addc_u32 s2, s35, s5
	s_mulk_i32 s2, 0xc0
	s_mul_hi_u32 s3, s1, 0xc0
	s_add_i32 s3, s3, s2
	s_mulk_i32 s1, 0xc0
	v_readlane_b32 s42, v250, 40
	v_readlane_b32 s43, v250, 41
	s_add_u32 s2, s42, s1
	s_mul_i32 s1, s35, 0xc0
	s_mul_hi_u32 s6, s34, 0xc0
	s_addc_u32 s3, s43, s3
	s_add_i32 s25, s6, s1
	s_mul_i32 s39, s34, 0xc0
	v_readlane_b32 s34, v250, 38
	v_readlane_b32 s35, v250, 39
	s_add_u32 s34, s34, s39
	v_mov_b32_e32 v2, v199
	s_addc_u32 s35, s35, s25
	v_readlane_b32 s1, v249, 61
	v_lshlrev_b32_e32 v4, 4, v2
	global_load_dwordx4 v[130:133], v4, s[34:35]
	v_add_u32_e32 v8, 0x1000, v4
	global_load_dwordx4 v[134:137], v8, s[34:35]
	s_mul_hi_i32 s27, s26, s1
	s_mul_i32 s26, s26, s1
	s_lshl_b64 s[26:27], s[26:27], 1
	v_readlane_b32 s42, v250, 36
	v_ashrrev_i32_e32 v3, 3, v2
	v_readlane_b32 s6, v249, 63
	v_readlane_b32 s43, v250, 37
	s_add_u32 s26, s42, s26
	v_and_b32_e32 v6, 0x70, v4
	v_mul_lo_u32 v0, v3, s6
	s_addc_u32 s27, s43, s27
	v_add_u32_e32 v10, 0x2000, v4
	v_or_b32_e32 v12, v6, v0
	v_bfe_u32 v230, v2, 5, 1
	global_load_dwordx4 v[138:141], v10, s[34:35]
	v_add_u32_e32 v14, s1, v12
	global_load_dwordx4 v[146:149], v12, s[26:27]
	global_load_dwordx4 v[170:173], v14, s[26:27]
	v_lshlrev_b32_e32 v0, 4, v230
	v_and_b32_e32 v204, 0xffffffdf, v2
	v_lshl_add_u64 v[16:17], s[2:3], 0, v[0:1]
	s_movk_i32 s1, 0xc0
	v_or_b32_e32 v202, 32, v2
	v_mad_i64_i32 v[18:19], s[2:3], v204, s1, v[16:17]
	v_mad_i64_i32 v[16:17], s[2:3], v202, s1, v[16:17]
	global_load_dwordx4 v[142:145], v[18:19], off
	global_load_dwordx4 v[150:153], v[18:19], off offset:32
	global_load_dwordx4 v[154:157], v[18:19], off offset:64
	global_load_dwordx4 v[158:161], v[18:19], off offset:96
	global_load_dwordx4 v[162:165], v[18:19], off offset:128
	global_load_dwordx4 v[166:169], v[18:19], off offset:160
	global_load_dwordx4 v[174:177], v[16:17], off
	global_load_dwordx4 v[178:181], v[16:17], off offset:32
	global_load_dwordx4 v[182:185], v[16:17], off offset:64
	global_load_dwordx4 v[186:189], v[16:17], off offset:96
	global_load_dwordx4 v[190:193], v[16:17], off offset:128
	global_load_dwordx4 v[194:197], v[16:17], off offset:160
	s_mov_b32 s1, 0x2aaaaaab
	v_mul_hi_i32 v5, v2, s1
	v_lshrrev_b32_e32 v7, 31, v5
	v_ashrrev_i32_e32 v5, 1, v5
	v_add_u32_e32 v5, v5, v7
	s_movk_i32 s6, 0xd0
	v_mad_u64_u32 v[16:17], s[2:3], v5, -12, v[2:3]
	v_mul_lo_u32 v5, v5, s6
	v_lshl_add_u32 v231, v16, 4, v5
	v_add_u32_e32 v16, 0x100, v2
	v_mul_hi_i32 v5, v16, s1
	v_lshrrev_b32_e32 v7, 31, v5
	v_ashrrev_i32_e32 v5, 1, v5
	v_add_u32_e32 v5, v5, v7
	v_mad_u64_u32 v[16:17], s[2:3], v5, -12, v[16:17]
	v_mul_lo_u32 v5, v5, s6
	v_lshl_add_u32 v232, v16, 4, v5
	v_add_u32_e32 v16, 0x200, v2
	v_mul_hi_i32 v5, v16, s1
	v_lshrrev_b32_e32 v7, 31, v5
	v_ashrrev_i32_e32 v5, 1, v5
	v_add_u32_e32 v5, v5, v7
	v_mad_u64_u32 v[16:17], s[2:3], v5, -12, v[16:17]
	v_mul_lo_u32 v5, v5, s6
	v_add_u32_e32 v7, 0, v231
	v_lshl_add_u32 v233, v16, 4, v5
	v_mov_b32_e32 v13, v1
	v_mov_b32_e32 v15, v1
	v_cmp_lt_i32_e32 vcc, v221, v220
	v_mov_b32_e32 v5, v1
	v_mov_b32_e32 v9, v1
	v_mov_b32_e32 v11, v1
	v_mov_b32_e32 v50, v1
	v_mov_b32_e32 v51, v1
	v_mov_b32_e32 v52, v1
	v_mov_b32_e32 v53, v1
	v_mov_b32_e32 v54, v1
	v_mov_b32_e32 v55, v1
	v_mov_b32_e32 v56, v1
	v_mov_b32_e32 v57, v1
	v_mov_b32_e32 v58, v1
	v_mov_b32_e32 v59, v1
	v_mov_b32_e32 v60, v1
	v_mov_b32_e32 v61, v1
	v_mov_b32_e32 v62, v1
	v_mov_b32_e32 v63, v1
	s_waitcnt vmcnt(16)
	ds_write_b128 v7, v[130:133]
	v_add_u32_e32 v7, 0, v232
	s_waitcnt vmcnt(15)
	ds_write_b128 v7, v[134:137]
	v_add_u32_e32 v7, 0, v233
	v_mad_u64_u32 v[206:207], s[2:3], v3, s16, v[6:7]
	s_lshl_b32 s2, s38, 3
	s_or_b32 s2, s40, s2
	s_lshl_b32 s3, s7, 3
	v_add_u32_e32 v3, 0, v206
	s_sub_i32 s2, s2, s3
	v_readlane_b32 s7, v248, 4
	s_mul_hi_i32 s3, s7, s2
	s_mul_i32 s2, s7, s2
	v_lshlrev_b32_e32 v6, 1, v2
	s_add_u32 s2, s2, 0x10d35980
	v_and_b32_e32 v6, 8, v6
	s_waitcnt vmcnt(14)
	ds_write_b128 v7, v[138:141]
	s_waitcnt vmcnt(13)
	ds_write_b128 v3, v[146:149] offset:13312
	s_waitcnt vmcnt(12)
; template <int DQK, bool BAND, int QT> ...
;     ...
;   float m[QT], l[QT];
; #pragma unroll
;   for (int qt = 0; qt < QT; ++qt) { m[qt] = -1e30f; l[qt] = 0.f; }
;   u32x4 rk[NKL], rv[2];
;   const int vrow0 = tid >> 3, vch = tid & 7;
;   unsigned klds[NKL];
; #pragma unroll
;   for (int i = 0; i < NKL; ++i) { const int idx = tid + i * 256, kr = idx / KV4, kc = idx - kr * KV4; klds[i] = kr * KROW + kc * 16; }
;   const unsigned koff0 = (unsigned)tid * 16u;
;   const unsigned voff0 = (unsigned)(vrow0 * ldv + vch * 8) * 2u, vstep = (unsigned)(32 * ldv) * 2u;
;   const unsigned vlds0 = KST + vrow0 * LROW + vch * 16;
;   auto gload = [&](int kt) {
;     const char* kb = (const char*)Kp + (size_t)kt * (DQK * 2);
;     const char* vb = (const char*)Vt + (size_t)kt * 2;
; #pragma unroll
;     for (int i = 0; i < NKL; ++i) rk[i] = *(const u32x4*)(kb + (koff0 + i * 4096u));
; #pragma unroll
;     for (int i = 0; i < 2; ++i) rv[i] = *(const u32x4*)(vb + (voff0 + i * vstep));
;   };
;   auto lstore = [&](char* st) {
; #pragma unroll
;     for (int i = 0; i < NKL; ++i) *(u32x4*)(st + klds[i]) = rk[i];
; #pragma unroll
;     for (int i = 0; i < 2; ++i) *(u32x4*)(st + vlds0 + i * 32 * LROW) = rv[i];
;   };
;   gload(kbeg);
;   lstore(lds);
;   __syncthreads();
;   const int pr = (ql & ~12) | ((ql & 4) << 1) | ((ql & 8) >> 1);
;   const int k_rd = pr * KROW + h * 16;
;   const int v_rd = KST + ql * LROW + h * 16;
;   const int qw0 = q0 + w * WQ;
	ds_write_b128 v3, v[170:173] offset:17920
	v_and_b32_e32 v3, 31, v2
	v_mul_u32_u24_e32 v234, 0x90, v3
	v_and_b32_e32 v3, 19, v2
	v_lshrrev_b32_e32 v2, 1, v2
	v_and_b32_e32 v2, 4, v2
	s_addc_u32 s3, s3, 0
	v_or3_b32 v2, v3, v6, v2
	v_lshl_add_u64 v[208:209], s[2:3], 0, v[12:13]
	v_lshl_add_u64 v[210:211], s[2:3], 0, v[14:15]
	s_add_u32 s2, s39, 0xf538900
	v_mul_u32_u24_e32 v235, 0xd0, v2
	v_cndmask_b32_e32 v2, v219, v221, vcc
	s_addc_u32 s3, s25, 0
	v_lshlrev_b32_e32 v203, 2, v2
	v_lshl_add_u64 v[212:213], s[2:3], 0, v[4:5]
	v_lshl_add_u64 v[214:215], s[2:3], 0, v[8:9]
	v_lshl_add_u64 v[216:217], s[2:3], 0, v[10:11]
	v_mov_b32_e32 v64, v1
	v_mov_b32_e32 v65, v1
	v_mov_b64_e32 v[18:19], v[50:51]
	v_mov_b64_e32 v[34:35], v[50:51]
	v_mov_b64_e32 v[2:3], v[50:51]
	s_mov_b32 s1, 0
	s_mov_b32 s6, 64
	v_mov_b32_e32 v237, 0xf149f2ca
	v_mov_b32_e32 v236, 0
	v_mov_b32_e32 v207, 0
	v_mov_b32_e32 v238, 0xf149f2ca
	v_mov_b64_e32 v[20:21], v[52:53]
	v_mov_b64_e32 v[22:23], v[54:55]
	v_mov_b64_e32 v[24:25], v[56:57]
	v_mov_b64_e32 v[26:27], v[58:59]
	v_mov_b64_e32 v[28:29], v[60:61]
	v_mov_b64_e32 v[30:31], v[62:63]
	v_mov_b64_e32 v[32:33], v[64:65]
	v_mov_b64_e32 v[36:37], v[52:53]
	v_mov_b64_e32 v[38:39], v[54:55]
	v_mov_b64_e32 v[40:41], v[56:57]
	v_mov_b64_e32 v[42:43], v[58:59]
	v_mov_b64_e32 v[44:45], v[60:61]
	v_mov_b64_e32 v[46:47], v[62:63]
	v_mov_b64_e32 v[48:49], v[64:65]
	v_mov_b64_e32 v[4:5], v[52:53]
	v_mov_b64_e32 v[6:7], v[54:55]
	v_mov_b64_e32 v[8:9], v[56:57]
	v_mov_b64_e32 v[10:11], v[58:59]
	v_mov_b64_e32 v[12:13], v[60:61]
	v_mov_b64_e32 v[14:15], v[62:63]
	v_mov_b64_e32 v[16:17], v[64:65]
	v_add_u32_e32 v235, v235, v0
	v_add_u32_e32 v234, v234, v0
	v_mbcnt_lo_u32_b32 v254, -1, 0
	v_mbcnt_hi_u32_b32 v254, -1, v254
	v_and_b32_e32 v255, 15, v254
	v_lshrrev_b32_e32 v253, 4, v254
	v_and_b32_e32 v253, 1, v253
	v_cmp_eq_u32_e32 vcc, v255, v253
	v_mov_b32_e32 v253, 0x3f803f80
	s_nop 1
	v_cndmask_b32_e32 v130, 0, v253, vcc
	v_mov_b32_e32 v131, v130
	v_mov_b32_e32 v132, v130
	v_mov_b32_e32 v133, v130
	v_mov_b32_e32 v134, 0
	v_mov_b32_e32 v135, 0
	v_mov_b32_e32 v136, 0
	v_mov_b32_e32 v137, 0
	v_mov_b32_e32 v138, 0
	v_mov_b32_e32 v139, 0
	v_mov_b32_e32 v140, 0
	v_mov_b32_e32 v141, 0
	v_readfirstlane_b32 s38, v199
	s_lshr_b32 s38, s38, 6
	s_lshl_b32 s39, s38, 10
	v_readlane_b32 s25, v249, 63
	v_mov_b32_e32 v253, v199
	v_mul_u32_u24_e32 v254, 0x13b2, v253
	v_lshrrev_b32_e32 v254, 16, v254
	v_mul_u32_u24_e32 v255, 13, v254
	v_sub_u32_e32 v255, v253, v255
	v_min_u32_e32 v255, 11, v255
	v_mul_u32_u24_e32 v254, 0xc0, v254
	v_lshl_add_u32 v146, v255, 4, v254
	v_add_u32_e32 v253, 0x100, v199
	v_mul_u32_u24_e32 v254, 0x13b2, v253
	v_lshrrev_b32_e32 v254, 16, v254
	v_mul_u32_u24_e32 v255, 13, v254
	v_sub_u32_e32 v255, v253, v255
	v_min_u32_e32 v255, 11, v255
	v_mul_u32_u24_e32 v254, 0xc0, v254
	v_lshl_add_u32 v147, v255, 4, v254
	v_add_u32_e32 v253, 0x200, v199
	v_mul_u32_u24_e32 v254, 0x13b2, v253
	v_lshrrev_b32_e32 v254, 16, v254
	v_mul_u32_u24_e32 v255, 13, v254
	v_sub_u32_e32 v255, v253, v255
	v_min_u32_e32 v255, 11, v255
	v_mul_u32_u24_e32 v254, 0xc0, v254
	v_lshl_add_u32 v148, v255, 4, v254
	v_mov_b32_e32 v253, v199
	v_mul_u32_u24_e32 v254, 0x1c72, v253
	v_lshrrev_b32_e32 v254, 16, v254
	v_mul_u32_u24_e32 v255, 9, v254
	v_sub_u32_e32 v255, v253, v255
	v_min_u32_e32 v255, 7, v255
	v_mul_lo_u32 v254, v254, s25
	v_lshl_add_u32 v170, v255, 4, v254
	v_add_u32_e32 v253, 0x100, v199
	v_mul_u32_u24_e32 v254, 0x1c72, v253
	v_lshrrev_b32_e32 v254, 16, v254
	v_mul_u32_u24_e32 v255, 9, v254
	v_sub_u32_e32 v255, v253, v255
	v_min_u32_e32 v255, 7, v255
	v_mul_lo_u32 v254, v254, s25
	v_lshl_add_u32 v171, v255, 4, v254
	v_add_u32_e32 v253, 0x300, v199
	v_mul_u32_u24_e32 v254, 0x13b2, v253
	v_lshrrev_b32_e32 v254, 16, v254
	v_mul_u32_u24_e32 v255, 13, v254
	v_sub_u32_e32 v255, v253, v255
	v_min_u32_e32 v255, 11, v255
	v_mul_u32_u24_e32 v254, 0xc0, v254
	v_lshl_add_u32 v149, v255, 4, v254
	v_add_u32_e32 v253, 0x1c0, v199
	v_mul_u32_u24_e32 v254, 0x1c72, v253
	v_lshrrev_b32_e32 v254, 16, v254
	v_mul_u32_u24_e32 v255, 9, v254
	v_sub_u32_e32 v255, v253, v255
	v_min_u32_e32 v255, 7, v255
	v_mul_lo_u32 v254, v254, s25
	v_lshl_add_u32 v172, v255, 4, v254
	v_cmp_gt_u32_e32 vcc, 64, v199
	s_nop 1
	v_cndmask_b32_e32 v149, v172, v149, vcc
	v_readfirstlane_b32 s34, v212
	v_readfirstlane_b32 s35, v213
	s_add_u32 s34, s34, s94
	s_addc_u32 s35, s35, s95
	s_sub_u32 s34, s34, s39
	s_subb_u32 s35, s35, 0
	v_readfirstlane_b32 s26, v208
	v_readfirstlane_b32 s27, v209
	s_add_u32 s26, s26, s94
	s_addc_u32 s27, s27, s95
	s_mul_i32 s42, s38, s25
	s_lshl_b32 s42, s42, 3
	s_sub_u32 s26, s26, s42
	s_subb_u32 s27, s27, 0
	v_mov_b32_e32 v208, 0xf149f2ca
	v_mov_b32_e32 v209, 0xf149f2ca
	v_mov_b32_e32 v210, 0
	v_mov_b32_e32 v211, 0
	s_waitcnt vmcnt(0) lgkmcnt(0)
	s_barrier

; template <int DQK, bool BAND, int QT> ...
;     ...
;         float mx = s[0][qt][0];
; #pragma unroll
;         for (int r = 1; r < 16; ++r) mx = fmaxf(mx, s[0][qt][r]);
; #pragma unroll
;         for (int r = 0; r < 16; ++r) mx = fmaxf(mx, s[1][qt][r]);
;         mx = fmaxf(mx, __shfl_xor(mx, 32));
;         if (__builtin_amdgcn_ballot_w64(mx > m[qt] + th) != 0) {
;           const float mn = fmaxf(m[qt], mx);
;           const float alpha = __builtin_amdgcn_exp2f((m[qt] - mn) * cc);
;           m[qt] = mn;
;           l[qt] *= alpha;
; #pragma unroll
;           for (int r = 0; r < 16; ++r) { o[0][qt][r] *= alpha; o[1][qt][r] *= alpha; }
;         }
.Lmla_dma_noload:
	s_nop 7
	s_setprio 0
	v_max_f32_e32 v239, v82, v83
	v_max_f32_e32 v253, v114, v115
	v_max3_f32 v239, v239, v84, v85
	v_max3_f32 v253, v253, v116, v117
	v_max3_f32 v239, v239, v86, v87
	v_max3_f32 v253, v253, v118, v119
	v_max3_f32 v239, v239, v88, v89
	v_max3_f32 v253, v253, v120, v121
	v_max3_f32 v239, v239, v90, v91
	v_max3_f32 v253, v253, v122, v123
	v_max3_f32 v239, v239, v92, v93
	v_max3_f32 v253, v253, v124, v125
	v_max3_f32 v239, v239, v94, v95
	v_max3_f32 v253, v253, v126, v127
	v_max3_f32 v239, v239, v96, v97
	v_max3_f32 v253, v253, v128, v129
	v_max3_f32 v239, v239, v66, v67
	v_max3_f32 v253, v253, v98, v99
	v_max3_f32 v239, v239, v68, v69
	v_max3_f32 v253, v253, v100, v101
	v_max3_f32 v239, v239, v70, v71
	v_max3_f32 v253, v253, v102, v103
	v_max3_f32 v239, v239, v72, v73
	v_max3_f32 v253, v253, v104, v105
	v_max3_f32 v239, v239, v74, v75
	v_max3_f32 v253, v253, v106, v107
	v_max3_f32 v239, v239, v76, v77
	v_max3_f32 v253, v253, v108, v109
	v_max3_f32 v239, v239, v78, v79
	v_max3_f32 v253, v253, v110, v111
	v_max3_f32 v239, v239, v80, v81
	v_max3_f32 v253, v253, v112, v113
	v_cmp_gt_f32_e32 vcc, v239, v208
	s_cbranch_vccz .Lmla_nr0
	ds_bpermute_b32 v254, v203, v239
	s_waitcnt lgkmcnt(0)
	v_max_f32_e32 v254, v254, v254
	v_max_f32_e32 v239, v239, v254
	v_max_f32_e32 v254, v237, v237
	v_max_f32_e32 v239, v254, v239
	v_sub_f32_e32 v237, v237, v239
	v_mul_f32_e32 v237, 0x3e16c740, v237
	v_exp_f32_e32 v254, v237
	v_mov_b32_e32 v237, v239
	v_add_f32_e32 v208, 0x4259535f, v239
	v_mul_f32_e32 v210, 0xbe16c740, v239
	v_pk_mul_f32 v[64:65], v[64:65], v[254:255] op_sel_hi:[1,0]
	v_pk_mul_f32 v[62:63], v[62:63], v[254:255] op_sel_hi:[1,0]
	v_pk_mul_f32 v[60:61], v[60:61], v[254:255] op_sel_hi:[1,0]
	v_pk_mul_f32 v[58:59], v[58:59], v[254:255] op_sel_hi:[1,0]
	v_pk_mul_f32 v[56:57], v[56:57], v[254:255] op_sel_hi:[1,0]
	v_pk_mul_f32 v[54:55], v[54:55], v[254:255] op_sel_hi:[1,0]
	v_pk_mul_f32 v[52:53], v[52:53], v[254:255] op_sel_hi:[1,0]
	v_pk_mul_f32 v[50:51], v[50:51], v[254:255] op_sel_hi:[1,0]
	v_pk_mul_f32 v[48:49], v[48:49], v[254:255] op_sel_hi:[1,0]
	v_pk_mul_f32 v[46:47], v[46:47], v[254:255] op_sel_hi:[1,0]
	v_pk_mul_f32 v[44:45], v[44:45], v[254:255] op_sel_hi:[1,0]
	v_pk_mul_f32 v[42:43], v[42:43], v[254:255] op_sel_hi:[1,0]
	v_pk_mul_f32 v[40:41], v[40:41], v[254:255] op_sel_hi:[1,0]
	v_pk_mul_f32 v[38:39], v[38:39], v[254:255] op_sel_hi:[1,0]
	v_pk_mul_f32 v[36:37], v[36:37], v[254:255] op_sel_hi:[1,0]
	v_pk_mul_f32 v[34:35], v[34:35], v[254:255] op_sel_hi:[1,0]
	v_mbcnt_lo_u32_b32 v255, -1, 0
	v_mbcnt_hi_u32_b32 v255, -1, v255
	v_add_u32_e32 v255, 16, v255
	v_lshlrev_b32_e32 v255, 2, v255
	ds_bpermute_b32 v255, v255, v254
	s_waitcnt lgkmcnt(0)
	v_mul_f32_e32 v134, v134, v254
	v_mul_f32_e32 v135, v135, v255
.Lmla_nr0:
	v_cmp_gt_f32_e32 vcc, v253, v209
	s_cbranch_vccz .Lmla_nr1
	ds_bpermute_b32 v254, v203, v253
	s_waitcnt lgkmcnt(0)
	v_max_f32_e32 v254, v254, v254
	v_max_f32_e32 v253, v253, v254
	v_max_f32_e32 v254, v238, v238
	v_max_f32_e32 v253, v254, v253
	v_sub_f32_e32 v238, v238, v253
	v_mul_f32_e32 v238, 0x3e16c740, v238
	v_exp_f32_e32 v254, v238
	v_mov_b32_e32 v238, v253
	v_add_f32_e32 v209, 0x4259535f, v253
	v_mul_f32_e32 v211, 0xbe16c740, v253
	v_pk_mul_f32 v[32:33], v[32:33], v[254:255] op_sel_hi:[1,0]
	v_pk_mul_f32 v[30:31], v[30:31], v[254:255] op_sel_hi:[1,0]
	v_pk_mul_f32 v[28:29], v[28:29], v[254:255] op_sel_hi:[1,0]
	v_pk_mul_f32 v[26:27], v[26:27], v[254:255] op_sel_hi:[1,0]
	v_pk_mul_f32 v[24:25], v[24:25], v[254:255] op_sel_hi:[1,0]
	v_pk_mul_f32 v[22:23], v[22:23], v[254:255] op_sel_hi:[1,0]
	v_pk_mul_f32 v[20:21], v[20:21], v[254:255] op_sel_hi:[1,0]
	v_pk_mul_f32 v[18:19], v[18:19], v[254:255] op_sel_hi:[1,0]
	v_pk_mul_f32 v[16:17], v[16:17], v[254:255] op_sel_hi:[1,0]
	v_pk_mul_f32 v[14:15], v[14:15], v[254:255] op_sel_hi:[1,0]
	v_pk_mul_f32 v[12:13], v[12:13], v[254:255] op_sel_hi:[1,0]
	v_pk_mul_f32 v[10:11], v[10:11], v[254:255] op_sel_hi:[1,0]
	v_pk_mul_f32 v[8:9], v[8:9], v[254:255] op_sel_hi:[1,0]
	v_pk_mul_f32 v[6:7], v[6:7], v[254:255] op_sel_hi:[1,0]
	v_pk_mul_f32 v[4:5], v[4:5], v[254:255] op_sel_hi:[1,0]
	v_pk_mul_f32 v[2:3], v[2:3], v[254:255] op_sel_hi:[1,0]
	v_mbcnt_lo_u32_b32 v255, -1, 0
	v_mbcnt_hi_u32_b32 v255, -1, v255
	v_add_u32_e32 v255, 16, v255
	v_lshlrev_b32_e32 v255, 2, v255
	ds_bpermute_b32 v255, v255, v254
	s_waitcnt lgkmcnt(0)
	v_mul_f32_e32 v138, v138, v254
	v_mul_f32_e32 v139, v139, v255
; DI unsigned pk2(float a, float b) { f32x2 v = {a, b}; bf16x2_t r = __builtin_convertvector(v, bf16x2_t); return __builtin_bit_cast(unsigned, r); }
; template <int DQK, bool BAND, int QT> ...
;     ...
;         const float mc = -m[qt] * cc;
;         float ls = 0.f;
; #pragma unroll
;         for (int a = 0; a < 2; ++a) {
; #pragma unroll
;           for (int r = 0; r < 16; ++r) { const float pv = __builtin_amdgcn_exp2f(fmaf(s[a][qt][r], cc, mc)); s[a][qt][r] = pv; ls += pv; }
; #pragma unroll
;           for (int s2 = 0; s2 < 2; ++s2) {
;             u32x4 pk;
;             pk.x = pk2(s[a][qt][8 * s2 + 0], s[a][qt][8 * s2 + 1]);
;             pk.y = pk2(s[a][qt][8 * s2 + 2], s[a][qt][8 * s2 + 3]);
;             pk.z = pk2(s[a][qt][8 * s2 + 4], s[a][qt][8 * s2 + 5]);
;             pk.w = pk2(s[a][qt][8 * s2 + 6], s[a][qt][8 * s2 + 7]);
;             pf[qt][a * 2 + s2] = __builtin_bit_cast(bf16x8, pk);
;           }
;         }
.Lmla_nr1:
	v_fmamk_f32 v82, v82, 0x3e16c740, v210
	v_fmamk_f32 v114, v114, 0x3e16c740, v211
	v_fmamk_f32 v83, v83, 0x3e16c740, v210
	v_fmamk_f32 v115, v115, 0x3e16c740, v211
	v_fmamk_f32 v84, v84, 0x3e16c740, v210
	v_fmamk_f32 v116, v116, 0x3e16c740, v211
	v_fmamk_f32 v85, v85, 0x3e16c740, v210
	v_fmamk_f32 v117, v117, 0x3e16c740, v211
	v_fmamk_f32 v86, v86, 0x3e16c740, v210
	v_fmamk_f32 v118, v118, 0x3e16c740, v211
	v_fmamk_f32 v87, v87, 0x3e16c740, v210
	v_fmamk_f32 v119, v119, 0x3e16c740, v211
	v_fmamk_f32 v88, v88, 0x3e16c740, v210
	v_fmamk_f32 v120, v120, 0x3e16c740, v211
	v_fmamk_f32 v89, v89, 0x3e16c740, v210
	v_fmamk_f32 v121, v121, 0x3e16c740, v211
	v_exp_f32_e32 v82, v82
	v_exp_f32_e32 v114, v114
	v_exp_f32_e32 v83, v83
	v_exp_f32_e32 v115, v115
	v_exp_f32_e32 v84, v84
	v_exp_f32_e32 v116, v116
	v_exp_f32_e32 v85, v85
	v_exp_f32_e32 v117, v117
	v_exp_f32_e32 v86, v86
	v_exp_f32_e32 v118, v118
	v_exp_f32_e32 v87, v87
	v_exp_f32_e32 v119, v119
	v_exp_f32_e32 v88, v88
	v_exp_f32_e32 v120, v120
	v_exp_f32_e32 v89, v89
	v_exp_f32_e32 v121, v121
	v_fmamk_f32 v90, v90, 0x3e16c740, v210
	v_fmamk_f32 v122, v122, 0x3e16c740, v211
	v_fmamk_f32 v91, v91, 0x3e16c740, v210
	v_fmamk_f32 v123, v123, 0x3e16c740, v211
	v_fmamk_f32 v92, v92, 0x3e16c740, v210
	v_fmamk_f32 v124, v124, 0x3e16c740, v211
	v_fmamk_f32 v93, v93, 0x3e16c740, v210
	v_fmamk_f32 v125, v125, 0x3e16c740, v211
	v_fmamk_f32 v94, v94, 0x3e16c740, v210
	v_fmamk_f32 v126, v126, 0x3e16c740, v211
	v_fmamk_f32 v95, v95, 0x3e16c740, v210
	v_fmamk_f32 v127, v127, 0x3e16c740, v211
	v_fmamk_f32 v96, v96, 0x3e16c740, v210
	v_fmamk_f32 v128, v128, 0x3e16c740, v211
	v_fmamk_f32 v97, v97, 0x3e16c740, v210
	v_fmamk_f32 v129, v129, 0x3e16c740, v211
	v_exp_f32_e32 v90, v90
	v_exp_f32_e32 v122, v122
	v_exp_f32_e32 v91, v91
	v_exp_f32_e32 v123, v123
	v_exp_f32_e32 v92, v92
	v_exp_f32_e32 v124, v124
	v_exp_f32_e32 v93, v93
	v_exp_f32_e32 v125, v125
	v_exp_f32_e32 v94, v94
	v_exp_f32_e32 v126, v126
	v_exp_f32_e32 v95, v95
	v_exp_f32_e32 v127, v127
	v_exp_f32_e32 v96, v96
	v_exp_f32_e32 v128, v128
	v_exp_f32_e32 v97, v97
	v_exp_f32_e32 v129, v129
	v_cvt_pk_bf16_f32 v82, v82, v83
	v_cvt_pk_bf16_f32 v114, v114, v115
	v_cvt_pk_bf16_f32 v83, v84, v85
	v_cvt_pk_bf16_f32 v115, v116, v117
	v_cvt_pk_bf16_f32 v84, v86, v87
	v_cvt_pk_bf16_f32 v116, v118, v119
	v_cvt_pk_bf16_f32 v85, v88, v89
	v_cvt_pk_bf16_f32 v117, v120, v121
	v_fmamk_f32 v66, v66, 0x3e16c740, v210
	v_fmamk_f32 v98, v98, 0x3e16c740, v211
	v_fmamk_f32 v67, v67, 0x3e16c740, v210
	v_fmamk_f32 v99, v99, 0x3e16c740, v211
	v_fmamk_f32 v68, v68, 0x3e16c740, v210
	v_fmamk_f32 v100, v100, 0x3e16c740, v211
	v_fmamk_f32 v69, v69, 0x3e16c740, v210
	v_fmamk_f32 v101, v101, 0x3e16c740, v211
	v_fmamk_f32 v70, v70, 0x3e16c740, v210
	v_fmamk_f32 v102, v102, 0x3e16c740, v211
	v_fmamk_f32 v71, v71, 0x3e16c740, v210
	v_fmamk_f32 v103, v103, 0x3e16c740, v211
	v_fmamk_f32 v72, v72, 0x3e16c740, v210
	v_fmamk_f32 v104, v104, 0x3e16c740, v211
	v_fmamk_f32 v73, v73, 0x3e16c740, v210
	v_fmamk_f32 v105, v105, 0x3e16c740, v211
	v_exp_f32_e32 v66, v66
	v_exp_f32_e32 v98, v98
	v_exp_f32_e32 v67, v67
	v_exp_f32_e32 v99, v99
	v_exp_f32_e32 v68, v68
	v_exp_f32_e32 v100, v100
	v_exp_f32_e32 v69, v69
	v_exp_f32_e32 v101, v101
	v_exp_f32_e32 v70, v70
	v_exp_f32_e32 v102, v102
	v_exp_f32_e32 v71, v71
	v_exp_f32_e32 v103, v103
	v_exp_f32_e32 v72, v72
	v_exp_f32_e32 v104, v104
	v_exp_f32_e32 v73, v73
	v_exp_f32_e32 v105, v105
	v_cvt_pk_bf16_f32 v90, v90, v91
	v_cvt_pk_bf16_f32 v122, v122, v123
	v_cvt_pk_bf16_f32 v91, v92, v93
	v_cvt_pk_bf16_f32 v123, v124, v125
	v_cvt_pk_bf16_f32 v92, v94, v95
	v_cvt_pk_bf16_f32 v124, v126, v127
	v_cvt_pk_bf16_f32 v93, v96, v97
	v_cvt_pk_bf16_f32 v125, v128, v129
	v_fmamk_f32 v74, v74, 0x3e16c740, v210
	v_fmamk_f32 v106, v106, 0x3e16c740, v211
	v_fmamk_f32 v75, v75, 0x3e16c740, v210
	v_fmamk_f32 v107, v107, 0x3e16c740, v211
	v_fmamk_f32 v76, v76, 0x3e16c740, v210
	v_fmamk_f32 v108, v108, 0x3e16c740, v211
	v_fmamk_f32 v77, v77, 0x3e16c740, v210
	v_fmamk_f32 v109, v109, 0x3e16c740, v211
	v_fmamk_f32 v78, v78, 0x3e16c740, v210
	v_fmamk_f32 v110, v110, 0x3e16c740, v211
	v_fmamk_f32 v79, v79, 0x3e16c740, v210
	v_fmamk_f32 v111, v111, 0x3e16c740, v211
	v_fmamk_f32 v80, v80, 0x3e16c740, v210
	v_fmamk_f32 v112, v112, 0x3e16c740, v211
	v_fmamk_f32 v81, v81, 0x3e16c740, v210
	v_fmamk_f32 v113, v113, 0x3e16c740, v211
	v_exp_f32_e32 v74, v74
	v_exp_f32_e32 v106, v106
	v_exp_f32_e32 v75, v75
	v_exp_f32_e32 v107, v107
	v_exp_f32_e32 v76, v76
	v_exp_f32_e32 v108, v108
	v_exp_f32_e32 v77, v77
	v_exp_f32_e32 v109, v109
	v_exp_f32_e32 v78, v78
	v_exp_f32_e32 v110, v110
	v_exp_f32_e32 v79, v79
	v_exp_f32_e32 v111, v111
	v_exp_f32_e32 v80, v80
	v_exp_f32_e32 v112, v112
	v_exp_f32_e32 v81, v81
	v_exp_f32_e32 v113, v113
	v_cvt_pk_bf16_f32 v66, v66, v67
	v_cvt_pk_bf16_f32 v98, v98, v99
	v_cvt_pk_bf16_f32 v67, v68, v69
	v_cvt_pk_bf16_f32 v99, v100, v101
	v_cvt_pk_bf16_f32 v68, v70, v71
	v_cvt_pk_bf16_f32 v100, v102, v103
	v_cvt_pk_bf16_f32 v69, v72, v73
	v_cvt_pk_bf16_f32 v101, v104, v105
	v_cvt_pk_bf16_f32 v74, v74, v75
	v_cvt_pk_bf16_f32 v106, v106, v107
	v_cvt_pk_bf16_f32 v75, v76, v77
	v_cvt_pk_bf16_f32 v107, v108, v109
	v_cvt_pk_bf16_f32 v76, v78, v79
	v_cvt_pk_bf16_f32 v108, v110, v111
	v_cvt_pk_bf16_f32 v77, v80, v81
	v_cvt_pk_bf16_f32 v109, v112, v113
	s_setprio 2
	ds_read_b128 v[86:89], v234 offset:13312
	ds_read_b128 v[94:97], v234 offset:17920
	ds_read_b128 v[70:73], v234 offset:13344
	ds_read_b128 v[78:81], v234 offset:17952
	ds_read_b128 v[118:121], v234 offset:13376
	ds_read_b128 v[126:129], v234 offset:17984
	ds_read_b128 v[102:105], v234 offset:13408
	ds_read_b128 v[110:113], v234 offset:18016
	s_waitcnt lgkmcnt(7)
; #define MFMA(a, b, c) __builtin_amdgcn_mfma_f32_32x32x16_bf16((a), (b), (c), 0, 0, 0)
; template <int DQK, bool BAND, int QT> ...
;     ...
; #pragma unroll
;       for (int ks = 0; ks < 4; ++ks) {
;         const bf16x8 v0 = *(const bf16x8*)(st + v_rd + ks * 32);
;         const bf16x8 v1 = *(const bf16x8*)(st + v_rd + 32 * LROW + ks * 32);
; #pragma unroll
;         for (int qt = 0; qt < QT; ++qt) {
;           o[0][qt] = MFMA(v0, pf[qt][ks], o[0][qt]);
;           o[1][qt] = MFMA(v1, pf[qt][ks], o[1][qt]);
;         }
;       }
;     } else {
;       if (more) lstore(lds + ((it + 1) & 1) * ST);
;     }
;     __syncthreads();
;   }
; #pragma unroll
;   for (int qt = 0; qt < QT; ++qt) {
;     const float lt = l[qt] + __shfl_xor(l[qt], 32);
;     const float inv = __builtin_amdgcn_rcpf(lt);
	v_mfma_f32_32x32x16_bf16 v[50:65], v[86:89], v[82:85], v[50:65]
	v_mfma_f32_32x32x16_bf16 v[18:33], v[86:89], v[114:117], v[18:33]
	s_waitcnt lgkmcnt(6)
	v_mfma_f32_32x32x16_bf16 v[34:49], v[94:97], v[82:85], v[34:49]
	v_mfma_f32_32x32x16_bf16 v[2:17], v[94:97], v[114:117], v[2:17]
	v_mfma_f32_16x16x32_bf16 v[134:137], v[130:133], v[82:85], v[134:137]
	v_mfma_f32_16x16x32_bf16 v[138:141], v[130:133], v[114:117], v[138:141]
	s_waitcnt lgkmcnt(5)
	v_mfma_f32_32x32x16_bf16 v[50:65], v[70:73], v[90:93], v[50:65]
	v_mfma_f32_32x32x16_bf16 v[18:33], v[70:73], v[122:125], v[18:33]
	s_waitcnt lgkmcnt(4)
	v_mfma_f32_32x32x16_bf16 v[34:49], v[78:81], v[90:93], v[34:49]
	v_mfma_f32_32x32x16_bf16 v[2:17], v[78:81], v[122:125], v[2:17]
	v_mfma_f32_16x16x32_bf16 v[134:137], v[130:133], v[90:93], v[134:137]
	v_mfma_f32_16x16x32_bf16 v[138:141], v[130:133], v[122:125], v[138:141]
	s_waitcnt lgkmcnt(3)
	v_mfma_f32_32x32x16_bf16 v[50:65], v[118:121], v[66:69], v[50:65]
	v_mfma_f32_32x32x16_bf16 v[18:33], v[118:121], v[98:101], v[18:33]
	s_waitcnt lgkmcnt(2)
	v_mfma_f32_32x32x16_bf16 v[34:49], v[126:129], v[66:69], v[34:49]
	v_mfma_f32_32x32x16_bf16 v[2:17], v[126:129], v[98:101], v[2:17]
	v_mfma_f32_16x16x32_bf16 v[134:137], v[130:133], v[66:69], v[134:137]
	v_mfma_f32_16x16x32_bf16 v[138:141], v[130:133], v[98:101], v[138:141]
	s_bitcmp1_b32 s1, 0
	s_cselect_b32 s7, -1, 1
	s_mulk_i32 s7, 0x5800
	v_add_u32_e32 v235, s7, v235
	v_add_u32_e32 v234, s7, v234
	s_add_i32 s1, s1, 1
	s_add_i32 s6, s6, 64
	s_waitcnt vmcnt(0) lgkmcnt(0)
	s_barrier
	v_mfma_f32_32x32x16_bf16 v[50:65], v[102:105], v[74:77], v[50:65]
	v_mfma_f32_32x32x16_bf16 v[18:33], v[102:105], v[106:109], v[18:33]
	v_mfma_f32_32x32x16_bf16 v[34:49], v[110:113], v[74:77], v[34:49]
	v_mfma_f32_32x32x16_bf16 v[2:17], v[110:113], v[106:109], v[2:17]
	v_mfma_f32_16x16x32_bf16 v[134:137], v[130:133], v[74:77], v[134:137]
	v_mfma_f32_16x16x32_bf16 v[138:141], v[130:133], v[106:109], v[138:141]
	s_cmp_lg_u32 s21, s1
	s_cbranch_scc1 .Lmla_top
	s_setprio 0
	s_nop 7
	v_mbcnt_lo_u32_b32 v254, -1, 0
	v_mbcnt_hi_u32_b32 v254, -1, v254
	v_and_b32_e32 v255, 15, v254
	v_lshlrev_b32_e32 v255, 2, v255
	ds_bpermute_b32 v239, v255, v134
	ds_bpermute_b32 v253, v255, v135
	s_waitcnt lgkmcnt(0)
	v_cmp_gt_u32_e32 vcc, 16, v254
	s_nop 1
	v_cndmask_b32_e32 v236, v253, v239, vcc
	v_cmp_gt_u32_e32 vcc, 32, v254
	s_nop 1
	v_cndmask_b32_e32 v236, 0, v236, vcc
	ds_bpermute_b32 v239, v255, v138
	ds_bpermute_b32 v253, v255, v139
	s_waitcnt lgkmcnt(0)
	v_cmp_gt_u32_e32 vcc, 16, v254
	s_nop 1
	v_cndmask_b32_e32 v207, v253, v239, vcc
	v_cmp_gt_u32_e32 vcc, 32, v254
	s_nop 1
	v_cndmask_b32_e32 v207, 0, v207, vcc
	s_branch .LBB0_663
	s_nop 0
